# one-unit phases: S4 (EpiGlu) per-block vmcnt(0) hoisted to one wait per load group; KV (EpiKV) rsmem row loads issued together
# baseline (speedup 1.0000x reference)
.LBB7_334:
	s_nop 0
	v_lshl_add_u64 v[128:129], v[168:169], 2, s[8:9]
	global_load_dword v132, v[128:129], off
	global_load_dword v225, v[128:129], off offset:64
	global_load_dword v226, v[128:129], off offset:128
	global_load_dword v227, v[128:129], off offset:192
	global_load_dword v228, v[128:129], off offset:512
	global_load_dword v229, v[128:129], off offset:576
	global_load_dword v230, v[128:129], off offset:640
	global_load_dword v231, v[128:129], off offset:704
	v_readlane_b32 s40, v251, 10
	s_add_u32 s38, s40, s38
	v_readlane_b32 s40, v251, 11
	s_addc_u32 s39, s40, s39
	v_lshlrev_b64 v[130:131], 11, v[168:169]
	v_lshl_add_u64 v[136:137], v[166:167], 1, s[38:39]
	v_lshl_add_u64 v[130:131], v[136:137], 0, v[130:131]
	v_lshl_add_u64 v[134:135], v[164:165], 2, s[8:9]
	s_mov_b64 s[38:39], 0x40000
	s_waitcnt vmcnt(0)
	v_pk_mul_f32 v[126:127], v[126:127], v[132:133] op_sel_hi:[1,0]
	v_pk_mul_f32 v[124:125], v[124:125], v[132:133] op_sel_hi:[1,0]
	v_pk_mul_f32 v[122:123], v[122:123], v[132:133] op_sel_hi:[1,0]
	v_pk_mul_f32 v[120:121], v[120:121], v[132:133] op_sel_hi:[1,0]
	v_pk_mul_f32 v[118:119], v[118:119], v[132:133] op_sel_hi:[1,0]
	v_pk_mul_f32 v[116:117], v[116:117], v[132:133] op_sel_hi:[1,0]
	v_pk_mul_f32 v[138:139], v[114:115], v[132:133] op_sel_hi:[1,0]
	v_pk_mul_f32 v[132:133], v[112:113], v[132:133] op_sel_hi:[1,0]
	v_cvt_pk_bf16_f32 v112, v124, v125
	v_cvt_pk_bf16_f32 v113, v126, v127
	v_cvt_pk_bf16_f32 v114, v120, v121
	v_cvt_pk_bf16_f32 v115, v122, v123
	global_store_dwordx4 v[130:131], v[112:115], off
	s_nop 1
	v_cvt_pk_bf16_f32 v112, v116, v117
	v_cvt_pk_bf16_f32 v113, v118, v119
	v_cvt_pk_bf16_f32 v114, v132, v133
	v_cvt_pk_bf16_f32 v115, v138, v139
	global_store_dwordx4 v[130:131], v[112:115], off offset:256
	s_nop 1
	v_lshl_add_u64 v[116:117], v[162:163], 2, s[8:9]
	v_lshlrev_b64 v[114:115], 11, v[164:165]
	v_lshl_add_u64 v[114:115], v[136:137], 0, v[114:115]
	v_mov_b32_e32 v112, v225
	v_pk_mul_f32 v[110:111], v[110:111], v[112:113] op_sel_hi:[1,0]
	v_pk_mul_f32 v[108:109], v[108:109], v[112:113] op_sel_hi:[1,0]
	v_pk_mul_f32 v[106:107], v[106:107], v[112:113] op_sel_hi:[1,0]
	v_pk_mul_f32 v[104:105], v[104:105], v[112:113] op_sel_hi:[1,0]
	v_pk_mul_f32 v[102:103], v[102:103], v[112:113] op_sel_hi:[1,0]
	v_pk_mul_f32 v[100:101], v[100:101], v[112:113] op_sel_hi:[1,0]
	v_pk_mul_f32 v[118:119], v[98:99], v[112:113] op_sel_hi:[1,0]
	v_pk_mul_f32 v[112:113], v[96:97], v[112:113] op_sel_hi:[1,0]
	v_cvt_pk_bf16_f32 v96, v108, v109
	v_cvt_pk_bf16_f32 v97, v110, v111
	v_cvt_pk_bf16_f32 v98, v104, v105
	v_cvt_pk_bf16_f32 v99, v106, v107
	global_store_dwordx4 v[114:115], v[96:99], off
	s_nop 1
	v_cvt_pk_bf16_f32 v96, v100, v101
	v_cvt_pk_bf16_f32 v97, v102, v103
	v_cvt_pk_bf16_f32 v98, v112, v113
	v_cvt_pk_bf16_f32 v99, v118, v119
	global_store_dwordx4 v[114:115], v[96:99], off offset:256
	s_nop 1
	v_lshl_add_u64 v[100:101], v[160:161], 2, s[8:9]
	v_lshlrev_b64 v[98:99], 11, v[162:163]
	v_lshl_add_u64 v[98:99], v[136:137], 0, v[98:99]
	v_mov_b32_e32 v96, v226
	v_pk_mul_f32 v[94:95], v[94:95], v[96:97] op_sel_hi:[1,0]
	v_pk_mul_f32 v[92:93], v[92:93], v[96:97] op_sel_hi:[1,0]
	v_pk_mul_f32 v[90:91], v[90:91], v[96:97] op_sel_hi:[1,0]
	v_pk_mul_f32 v[88:89], v[88:89], v[96:97] op_sel_hi:[1,0]
	v_pk_mul_f32 v[86:87], v[86:87], v[96:97] op_sel_hi:[1,0]
	v_pk_mul_f32 v[84:85], v[84:85], v[96:97] op_sel_hi:[1,0]
	v_pk_mul_f32 v[102:103], v[82:83], v[96:97] op_sel_hi:[1,0]
	v_pk_mul_f32 v[96:97], v[80:81], v[96:97] op_sel_hi:[1,0]
	v_cvt_pk_bf16_f32 v80, v92, v93
	v_cvt_pk_bf16_f32 v81, v94, v95
	v_cvt_pk_bf16_f32 v82, v88, v89
	v_cvt_pk_bf16_f32 v83, v90, v91
	global_store_dwordx4 v[98:99], v[80:83], off
	s_nop 1
	v_cvt_pk_bf16_f32 v80, v84, v85
	v_cvt_pk_bf16_f32 v81, v86, v87
	v_cvt_pk_bf16_f32 v82, v96, v97
	v_cvt_pk_bf16_f32 v83, v102, v103
	global_store_dwordx4 v[98:99], v[80:83], off offset:256
	s_nop 1
	v_mov_b32_e32 v80, v227
	v_pk_mul_f32 v[78:79], v[78:79], v[80:81] op_sel_hi:[1,0]
	v_lshlrev_b64 v[82:83], 11, v[160:161]
	v_lshl_add_u64 v[82:83], v[136:137], 0, v[82:83]
	v_pk_mul_f32 v[76:77], v[76:77], v[80:81] op_sel_hi:[1,0]
	v_pk_mul_f32 v[74:75], v[74:75], v[80:81] op_sel_hi:[1,0]
	v_pk_mul_f32 v[72:73], v[72:73], v[80:81] op_sel_hi:[1,0]
	v_pk_mul_f32 v[70:71], v[70:71], v[80:81] op_sel_hi:[1,0]
	v_pk_mul_f32 v[68:69], v[68:69], v[80:81] op_sel_hi:[1,0]
	v_pk_mul_f32 v[84:85], v[66:67], v[80:81] op_sel_hi:[1,0]
	v_pk_mul_f32 v[80:81], v[64:65], v[80:81] op_sel_hi:[1,0]
	v_cvt_pk_bf16_f32 v64, v76, v77
	v_cvt_pk_bf16_f32 v65, v78, v79
	v_cvt_pk_bf16_f32 v66, v72, v73
	v_cvt_pk_bf16_f32 v67, v74, v75
	global_store_dwordx4 v[82:83], v[64:67], off
	s_nop 1
	v_cvt_pk_bf16_f32 v64, v68, v69
	v_cvt_pk_bf16_f32 v65, v70, v71
	v_cvt_pk_bf16_f32 v66, v80, v81
	v_cvt_pk_bf16_f32 v67, v84, v85
	global_store_dwordx4 v[82:83], v[64:67], off offset:256
	s_nop 1
	v_add_co_u32_e32 v68, vcc, s69, v130
	v_lshl_add_u64 v[66:67], v[130:131], 0, s[38:39]
	s_nop 0
	v_addc_co_u32_e32 v69, vcc, 0, v131, vcc
	v_mov_b32_e32 v64, v228
	v_pk_mul_f32 v[62:63], v[62:63], v[64:65] op_sel_hi:[1,0]
	v_pk_mul_f32 v[60:61], v[60:61], v[64:65] op_sel_hi:[1,0]
	v_pk_mul_f32 v[58:59], v[58:59], v[64:65] op_sel_hi:[1,0]
	v_pk_mul_f32 v[56:57], v[56:57], v[64:65] op_sel_hi:[1,0]
	v_pk_mul_f32 v[54:55], v[54:55], v[64:65] op_sel_hi:[1,0]
	v_pk_mul_f32 v[52:53], v[52:53], v[64:65] op_sel_hi:[1,0]
	v_pk_mul_f32 v[70:71], v[50:51], v[64:65] op_sel_hi:[1,0]
	v_pk_mul_f32 v[64:65], v[48:49], v[64:65] op_sel_hi:[1,0]
	v_cvt_pk_bf16_f32 v48, v60, v61
	v_cvt_pk_bf16_f32 v49, v62, v63
	v_cvt_pk_bf16_f32 v50, v56, v57
	v_cvt_pk_bf16_f32 v51, v58, v59
	global_store_dwordx4 v[68:69], v[48:51], off
	s_nop 1
	v_cvt_pk_bf16_f32 v48, v52, v53
	v_cvt_pk_bf16_f32 v49, v54, v55
	v_cvt_pk_bf16_f32 v50, v64, v65
	v_cvt_pk_bf16_f32 v51, v70, v71
	global_store_dwordx4 v[66:67], v[48:51], off offset:256
	s_nop 1
	v_add_co_u32_e32 v52, vcc, s70, v130
	v_lshl_add_u64 v[50:51], v[130:131], 0, s[24:25]
	s_nop 0
	v_addc_co_u32_e32 v53, vcc, 0, v131, vcc
	v_mov_b32_e32 v48, v229
	v_pk_mul_f32 v[46:47], v[46:47], v[48:49] op_sel_hi:[1,0]
	v_pk_mul_f32 v[44:45], v[44:45], v[48:49] op_sel_hi:[1,0]
	v_pk_mul_f32 v[42:43], v[42:43], v[48:49] op_sel_hi:[1,0]
	v_pk_mul_f32 v[40:41], v[40:41], v[48:49] op_sel_hi:[1,0]
	v_pk_mul_f32 v[38:39], v[38:39], v[48:49] op_sel_hi:[1,0]
	v_pk_mul_f32 v[36:37], v[36:37], v[48:49] op_sel_hi:[1,0]
	v_pk_mul_f32 v[54:55], v[34:35], v[48:49] op_sel_hi:[1,0]
	v_pk_mul_f32 v[48:49], v[32:33], v[48:49] op_sel_hi:[1,0]
	v_cvt_pk_bf16_f32 v32, v44, v45
	v_cvt_pk_bf16_f32 v33, v46, v47
	v_cvt_pk_bf16_f32 v34, v40, v41
	v_cvt_pk_bf16_f32 v35, v42, v43
	global_store_dwordx4 v[52:53], v[32:35], off
	s_nop 1
	v_cvt_pk_bf16_f32 v32, v36, v37
	v_cvt_pk_bf16_f32 v33, v38, v39
	v_cvt_pk_bf16_f32 v34, v48, v49
	v_cvt_pk_bf16_f32 v35, v54, v55
	global_store_dwordx4 v[50:51], v[32:35], off offset:256
	s_nop 1
	v_add_co_u32_e32 v36, vcc, s71, v130
	v_lshl_add_u64 v[34:35], v[130:131], 0, s[44:45]
	s_nop 0
	v_addc_co_u32_e32 v37, vcc, 0, v131, vcc
	v_mov_b32_e32 v32, v230
	v_pk_mul_f32 v[30:31], v[30:31], v[32:33] op_sel_hi:[1,0]
	v_pk_mul_f32 v[28:29], v[28:29], v[32:33] op_sel_hi:[1,0]
	v_pk_mul_f32 v[26:27], v[26:27], v[32:33] op_sel_hi:[1,0]
	v_pk_mul_f32 v[24:25], v[24:25], v[32:33] op_sel_hi:[1,0]
	v_pk_mul_f32 v[22:23], v[22:23], v[32:33] op_sel_hi:[1,0]
	v_pk_mul_f32 v[20:21], v[20:21], v[32:33] op_sel_hi:[1,0]
	v_pk_mul_f32 v[38:39], v[18:19], v[32:33] op_sel_hi:[1,0]
	v_pk_mul_f32 v[32:33], v[16:17], v[32:33] op_sel_hi:[1,0]
	v_cvt_pk_bf16_f32 v16, v28, v29
	v_cvt_pk_bf16_f32 v17, v30, v31
	v_cvt_pk_bf16_f32 v18, v24, v25
	v_cvt_pk_bf16_f32 v19, v26, v27
	global_store_dwordx4 v[36:37], v[16:19], off
	s_nop 1
	v_cvt_pk_bf16_f32 v16, v20, v21
	v_cvt_pk_bf16_f32 v17, v22, v23
	v_cvt_pk_bf16_f32 v18, v32, v33
	v_cvt_pk_bf16_f32 v19, v38, v39
	global_store_dwordx4 v[34:35], v[16:19], off offset:256
	s_nop 1
	v_add_co_u32_e32 v20, vcc, s72, v130
	v_lshl_add_u64 v[18:19], v[130:131], 0, s[28:29]
	s_nop 0
	v_addc_co_u32_e32 v21, vcc, 0, v131, vcc
	v_mov_b32_e32 v16, v231
	v_pk_mul_f32 v[14:15], v[14:15], v[16:17] op_sel_hi:[1,0]
	v_pk_mul_f32 v[12:13], v[12:13], v[16:17] op_sel_hi:[1,0]
	v_pk_mul_f32 v[10:11], v[10:11], v[16:17] op_sel_hi:[1,0]
	v_pk_mul_f32 v[8:9], v[8:9], v[16:17] op_sel_hi:[1,0]
	v_pk_mul_f32 v[6:7], v[6:7], v[16:17] op_sel_hi:[1,0]
	v_pk_mul_f32 v[4:5], v[4:5], v[16:17] op_sel_hi:[1,0]
	v_pk_mul_f32 v[22:23], v[2:3], v[16:17] op_sel_hi:[1,0]
	v_pk_mul_f32 v[16:17], v[0:1], v[16:17] op_sel_hi:[1,0]
	v_cvt_pk_bf16_f32 v0, v12, v13
	v_cvt_pk_bf16_f32 v1, v14, v15
	v_cvt_pk_bf16_f32 v2, v8, v9
	v_cvt_pk_bf16_f32 v3, v10, v11
	global_store_dwordx4 v[20:21], v[0:3], off
	s_nop 1
	v_cvt_pk_bf16_f32 v0, v4, v5
	v_cvt_pk_bf16_f32 v1, v6, v7
	v_cvt_pk_bf16_f32 v2, v16, v17
	v_cvt_pk_bf16_f32 v3, v22, v23
	global_store_dwordx4 v[18:19], v[0:3], off offset:256
	s_andn2_b64 vcc, exec, s[6:7]
	s_mov_b64 s[6:7], -1
	s_cbranch_vccnz .LBB7_319
